# up-GEMM epilogue: row-sum slot loads share one base pointer with immediate offsets (9 address instructions less per half)
# baseline (speedup 1.0000x reference)
; #define PG8_LAS __attribute__((address_space(3)))
; __device__ __forceinline__ float row_up1(float v) { return dpp_mov<0x111>(v); }
;     __device__ __forceinline__ void operator()(f32x4 (&acc)[2][2][4][2], const pg8::Unit& u, int wr, int wc, int fr, int fq) const {
;     ...
;         PG8_LAS unsigned char* wl = WL + (wr * 4 + wc) * 1024;
;         {
;             const int l = fq * 16 + fr, p = l >> 4, bj = (l >> 3) & 1, c4 = (l & 7) * 4;
;             const float* srcp = (p < 3 ? FW + p * NUP : FB) + bj * DFF + u.pn * 128 + wc * 32 + c4;
;             *(PG8_LAS f32x4*)(wl + l * 16) = *(const f32x4*)srcp;
;         }
; #pragma unroll
;         for (int ai = 0; ai < 2; ++ai) {
;             const int tb = u.pm * 256 + ai * 128 + wr * 64 + 4 * fr;
;             float rstd[4];
; #pragma unroll
;             for (int m = 0; m < 4; ++m) { const f32x4 sv = *(const f32x4*)(SS + (size_t)(tb + m) * 16 + 4 * fq); float s = (sv[0] + sv[1]) + (sv[2] + sv[3]); s += __shfl_xor(s, 16); s += __shfl_xor(s, 32);
;                 rstd[m] = rsqrtf(s * (1.0f / 1024.0f) + EPS); }
;             u32x2 pk[2][4];
; #pragma unroll
;             for (int n = 0; n < 2; ++n) {
;                 f32x4 g[4];
;                 {   const PG8_LAS unsigned char* wq = wl + (8 * fq + 4 * n) * 4;
;                     const f32x4 w0 = *(const PG8_LAS f32x4*)(wq), w1 = *(const PG8_LAS f32x4*)(wq + 256), w2 = *(const PG8_LAS f32x4*)(wq + 512), bb = *(const PG8_LAS f32x4*)(wq + 768);
;                     const f32x4 x0 = acc[ai][0][0][n] * rstd[0], x1 = acc[ai][0][1][n] * rstd[1], x2 = acc[ai][0][2][n] * rstd[2], x3 = acc[ai][0][3][n] * rstd[3];
;                     acc[ai][0][0][n] = x0; acc[ai][0][1][n] = x1; acc[ai][0][2][n] = x2; acc[ai][0][3][n] = x3;
;                     f32x4 p1, p2;
; #pragma unroll
;                     for (int c = 0; c < 4; ++c) { p1[c] = row_up1(x3[c]); p2[c] = row_up1(x2[c]); }
;                     g[0] = bb + w2 * x0 + w1 * p1 + w0 * p2; g[1] = bb + w2 * x1 + w1 * x0 + w0 * p1;
;                     g[2] = bb + w2 * x2 + w1 * x1 + w0 * x0; g[3] = bb + w2 * x3 + w1 * x2 + w0 * x1;
; #pragma unroll
;                     for (int m = 0; m < 4; ++m)
; #pragma unroll
;                         for (int c = 0; c < 4; ++c) g[m][c] = siluf_(g[m][c]);
.LBB0_748:
	v_lshl_add_u32 v148, s34, 8, v187
	v_ashrrev_i32_e32 v149, 31, v148
	v_lshlrev_b64 v[150:151], 6, v[148:149]
	v_lshl_add_u64 v[246:247], v[138:139], 0, v[150:151]
	v_or_b32_e32 v150, 1, v148
	global_load_dwordx4 v[160:163], v[246:247], off
	global_load_dwordx4 v[164:167], v[246:247], off offset:64
	v_or_b32_e32 v154, 2, v148
	global_load_dwordx4 v[172:175], v[246:247], off offset:128
	v_or_b32_e32 v156, 3, v148
	global_load_dwordx4 v[176:179], v[246:247], off offset:192
	s_lshl_b32 s8, s66, 7
	s_ashr_i32 s9, s8, 31
	v_lshl_add_u64 v[158:159], s[8:9], 2, v[136:137]
	global_load_dwordx4 v[180:183], v[158:159], off
	v_and_b32_e32 v151, 64, v194
	v_xor_b32_e32 v149, 16, v194
	v_add_u32_e32 v151, 64, v151
	v_cmp_lt_i32_e32 vcc, v149, v151
	v_xor_b32_e32 v155, 32, v194
	v_mov_b64_e32 v[184:185], s[38:39]
	v_cndmask_b32_e32 v149, v194, v149, vcc
	v_lshlrev_b32_e32 v149, 2, v149
	v_cmp_lt_i32_e32 vcc, v155, v151
	v_or_b32_e32 v158, s8, v186
	v_ashrrev_i32_e32 v159, 31, v158
	v_cndmask_b32_e32 v151, v194, v155, vcc
	v_lshlrev_b32_e32 v151, 2, v151
	s_waitcnt vmcnt(0)
	v_mov_b32_e32 v196, v161
	v_mov_b32_e32 v197, v162
	v_mov_b32_e32 v161, v163
	v_mov_b32_e32 v162, v165
	v_mov_b32_e32 v163, v166
	v_mov_b32_e32 v165, v167
	v_mov_b32_e32 v166, v173
	v_mov_b32_e32 v167, v174
	v_mov_b32_e32 v173, v175
	v_pk_add_f32 v[160:161], v[196:197], v[160:161]
	v_pk_add_f32 v[162:163], v[162:163], v[164:165]
	v_mov_b32_e32 v174, v177
	v_mov_b32_e32 v175, v178
	v_mov_b32_e32 v177, v179
	v_pk_add_f32 v[166:167], v[166:167], v[172:173]
	v_pk_add_f32 v[172:173], v[174:175], v[176:177]
	v_mov_b32_e32 v165, v160
	v_mov_b32_e32 v164, v162
	v_mov_b32_e32 v160, v163
	v_mov_b32_e32 v162, v172
	v_mov_b32_e32 v163, v166
	v_mov_b32_e32 v166, v173
	v_pk_add_f32 v[160:161], v[164:165], v[160:161]
	v_pk_add_f32 v[162:163], v[162:163], v[166:167]
	ds_bpermute_b32 v165, v149, v161
	ds_bpermute_b32 v164, v149, v160
	ds_bpermute_b32 v167, v149, v163
	ds_bpermute_b32 v166, v149, v162
	v_mul_f32_e32 v180, v239, v180
	v_mul_f32_e32 v181, v239, v181
	v_mul_f32_e32 v182, v239, v182
	v_mul_f32_e32 v183, v239, v183
	ds_write_b128 v193, v[180:183]
	s_waitcnt lgkmcnt(3)
	v_pk_add_f32 v[172:173], v[160:161], v[164:165]
	ds_bpermute_b32 v197, v151, v173
	s_waitcnt lgkmcnt(2)
	v_pk_add_f32 v[174:175], v[162:163], v[166:167]
	ds_bpermute_b32 v196, v151, v172
	ds_bpermute_b32 v199, v151, v175
	ds_bpermute_b32 v198, v151, v174
	ds_read_b128 v[160:163], v195
	ds_read_b128 v[164:167], v195 offset:256
	ds_read_b128 v[176:179], v195 offset:512
	ds_read_b128 v[180:183], v195 offset:768
	s_waitcnt lgkmcnt(6)
	v_pk_add_f32 v[172:173], v[172:173], v[196:197]
	s_nop 0
	v_pk_fma_f32 v[172:173], v[172:173], s[24:25], v[184:185] op_sel_hi:[1,0,0]
	s_waitcnt lgkmcnt(4)
	v_pk_add_f32 v[174:175], v[174:175], v[198:199]
	v_pk_fma_f32 v[174:175], v[174:175], s[24:25], v[184:185] op_sel_hi:[1,0,0]
	v_rsq_f32_e32 v155, v173
	v_rsq_f32_e32 v168, v175
	v_rsq_f32_e32 v173, v174
	v_rsq_f32_e32 v157, v172
	v_mov_b32_e32 v174, v155
	v_mov_b32_e32 v170, v168
	v_mov_b32_e32 v168, v173
	v_pk_mul_f32 v[124:125], v[124:125], v[174:175] op_sel_hi:[1,0]
	v_pk_mul_f32 v[112:113], v[112:113], v[168:169] op_sel_hi:[1,0]
	v_pk_mul_f32 v[116:117], v[116:117], v[170:171] op_sel_hi:[1,0]
	s_waitcnt lgkmcnt(0)
	v_pk_fma_f32 v[204:205], v[176:177], v[124:125], v[180:181]
	v_mov_b32_dpp v184, v112 row_shr:1 row_mask:0xf bank_mask:0xf bound_ctrl:1
	v_mov_b32_dpp v185, v113 row_shr:1 row_mask:0xf bank_mask:0xf bound_ctrl:1
	v_mov_b32_dpp v196, v116 row_shr:1 row_mask:0xf bank_mask:0xf bound_ctrl:1
	v_mov_b32_dpp v197, v117 row_shr:1 row_mask:0xf bank_mask:0xf bound_ctrl:1
	v_pk_fma_f32 v[204:205], v[164:165], v[184:185], v[204:205]
	v_pk_fma_f32 v[196:197], v[160:161], v[196:197], v[204:205]
	v_mov_b32_e32 v172, v157
	v_pk_mul_f32 v[126:127], v[126:127], v[174:175] op_sel_hi:[1,0]
	v_pk_mul_f32 v[120:121], v[120:121], v[172:173] op_sel_hi:[1,0]
	v_pk_mul_f32 v[114:115], v[114:115], v[168:169] op_sel_hi:[1,0]
	v_exp_f32_e32 v240, v196
	v_pk_mul_f32 v[118:119], v[118:119], v[170:171] op_sel_hi:[1,0]
	v_mov_b32_dpp v198, v114 row_shr:1 row_mask:0xf bank_mask:0xf bound_ctrl:1
	v_mov_b32_dpp v199, v115 row_shr:1 row_mask:0xf bank_mask:0xf bound_ctrl:1
	v_pk_fma_f32 v[202:203], v[178:179], v[126:127], v[182:183]
	v_pk_fma_f32 v[204:205], v[176:177], v[120:121], v[180:181]
	v_exp_f32_e32 v241, v197
	v_pk_mul_f32 v[122:123], v[122:123], v[172:173] op_sel_hi:[1,0]
	v_mov_b32_dpp v200, v118 row_shr:1 row_mask:0xf bank_mask:0xf bound_ctrl:1
	v_mov_b32_dpp v201, v119 row_shr:1 row_mask:0xf bank_mask:0xf bound_ctrl:1
	v_pk_fma_f32 v[202:203], v[166:167], v[198:199], v[202:203]
	v_pk_fma_f32 v[204:205], v[164:165], v[124:125], v[204:205]
	v_pk_fma_f32 v[200:201], v[162:163], v[200:201], v[202:203]
	v_pk_fma_f32 v[202:203], v[178:179], v[122:123], v[182:183]
	v_pk_fma_f32 v[184:185], v[160:161], v[184:185], v[204:205]
	v_pk_fma_f32 v[204:205], v[176:177], v[116:117], v[180:181]
	v_pk_fma_f32 v[176:177], v[176:177], v[112:113], v[180:181]
	v_pk_fma_f32 v[202:203], v[166:167], v[126:127], v[202:203]
	v_pk_fma_f32 v[204:205], v[164:165], v[120:121], v[204:205]
	v_pk_fma_f32 v[164:165], v[164:165], v[116:117], v[176:177]
	v_pk_fma_f32 v[198:199], v[162:163], v[198:199], v[202:203]
	v_pk_fma_f32 v[202:203], v[178:179], v[118:119], v[182:183]
	v_pk_fma_f32 v[204:205], v[160:161], v[124:125], v[204:205]
	v_pk_fma_f32 v[178:179], v[178:179], v[114:115], v[182:183]
	v_pk_fma_f32 v[214:215], v[160:161], v[120:121], v[164:165]
	v_pk_add_f32 v[240:241], v[240:241], v[250:251]
	v_rcp_f32_e32 v160, v240
	v_pk_fma_f32 v[202:203], v[166:167], v[122:123], v[202:203]
; #define PG8_LAS __attribute__((address_space(3)))
; __device__ __forceinline__ unsigned pk2(float a, float b) { return pg8::cvt_pk_bf16(a, b); }
; __device__ __forceinline__ float row_up1(float v) { return dpp_mov<0x111>(v); }
; __device__ __forceinline__ float siluf_(float x) { return x * __builtin_amdgcn_rcpf(1.0f + __builtin_amdgcn_exp2f(x * -1.4426950408889634f)); }
;     __device__ __forceinline__ void operator()(f32x4 (&acc)[2][2][4][2], const pg8::Unit& u, int wr, int wc, int fr, int fq) const {
;     ...
;                     g[0] = bb + w2 * x0 + w1 * p1 + w0 * p2; g[1] = bb + w2 * x1 + w1 * x0 + w0 * p1;
;                     g[2] = bb + w2 * x2 + w1 * x1 + w0 * x0; g[3] = bb + w2 * x3 + w1 * x2 + w0 * x1;
; #pragma unroll
;                     for (int m = 0; m < 4; ++m)
; #pragma unroll
;                         for (int c = 0; c < 4; ++c) g[m][c] = siluf_(g[m][c]);
;                 }
;                 __builtin_amdgcn_sched_barrier(0);
;                 {   const PG8_LAS unsigned char* wq = wl + 128 + (8 * fq + 4 * n) * 4;
;                     const f32x4 w0 = *(const PG8_LAS f32x4*)(wq), w1 = *(const PG8_LAS f32x4*)(wq + 256), w2 = *(const PG8_LAS f32x4*)(wq + 512), bb = *(const PG8_LAS f32x4*)(wq + 768);
;                     const f32x4 x0 = acc[ai][1][0][n] * rstd[0], x1 = acc[ai][1][1][n] * rstd[1], x2 = acc[ai][1][2][n] * rstd[2], x3 = acc[ai][1][3][n] * rstd[3];
;                     acc[ai][1][0][n] = x0; acc[ai][1][1][n] = x1; acc[ai][1][2][n] = x2; acc[ai][1][3][n] = x3;
;                     f32x4 p1, p2;
; #pragma unroll
;                     for (int c = 0; c < 4; ++c) { p1[c] = row_up1(x3[c]); p2[c] = row_up1(x2[c]); }
;                     g[0] *= bb + w2 * x0 + w1 * p1 + w0 * p2; g[1] *= bb + w2 * x1 + w1 * x0 + w0 * p1;
;                     g[2] *= bb + w2 * x2 + w1 * x1 + w0 * x0; g[3] *= bb + w2 * x3 + w1 * x2 + w0 * x1;
;                 }
; #pragma unroll
;                 for (int m = 0; m < 4; ++m) { pk[n][m].x = pk2(g[m][0], g[m][1]); pk[n][m].y = pk2(g[m][2], g[m][3]); }
	v_pk_fma_f32 v[166:167], v[166:167], v[118:119], v[178:179]
	v_exp_f32_e32 v242, v200
	v_pk_fma_f32 v[202:203], v[162:163], v[126:127], v[202:203]
	v_pk_fma_f32 v[212:213], v[162:163], v[122:123], v[166:167]
	v_exp_f32_e32 v243, v201
	v_rcp_f32_e32 v161, v241
	v_pk_add_f32 v[242:243], v[242:243], v[250:251]
	v_rcp_f32_e32 v162, v242
	v_rcp_f32_e32 v163, v243
	v_exp_f32_e32 v244, v184
	v_exp_f32_e32 v245, v185
	v_pk_mul_f32 v[216:217], v[196:197], v[160:161]
	v_pk_add_f32 v[244:245], v[244:245], v[250:251]
	v_rcp_f32_e32 v160, v244
	v_exp_f32_e32 v246, v198
	v_pk_mul_f32 v[218:219], v[200:201], v[162:163]
	v_exp_f32_e32 v247, v199
	v_rcp_f32_e32 v161, v245
	v_pk_add_f32 v[246:247], v[246:247], v[250:251]
	v_rcp_f32_e32 v162, v246
	v_rcp_f32_e32 v163, v247
	v_exp_f32_e32 v248, v204
	v_exp_f32_e32 v249, v205
	v_pk_mul_f32 v[184:185], v[184:185], v[160:161]
	v_pk_add_f32 v[248:249], v[248:249], v[250:251]
	v_rcp_f32_e32 v160, v248
	v_exp_f32_e32 v240, v202
	v_exp_f32_e32 v241, v203
	v_rcp_f32_e32 v161, v249
	v_pk_add_f32 v[240:241], v[240:241], v[250:251]
	v_rcp_f32_e32 v164, v240
	v_exp_f32_e32 v242, v214
	v_exp_f32_e32 v243, v215
	v_rcp_f32_e32 v165, v241
	v_pk_add_f32 v[242:243], v[242:243], v[250:251]
	v_rcp_f32_e32 v220, v242
	v_exp_f32_e32 v244, v212
	v_exp_f32_e32 v245, v213
	v_rcp_f32_e32 v221, v243
	v_pk_add_f32 v[244:245], v[244:245], v[250:251]
	v_rcp_f32_e32 v222, v244
	v_rcp_f32_e32 v223, v245
	v_pk_mul_f32 v[224:225], v[198:199], v[162:163]
	v_pk_mul_f32 v[226:227], v[204:205], v[160:161]
	v_pk_mul_f32 v[228:229], v[202:203], v[164:165]
	ds_read_b128 v[196:199], v195 offset:128
	ds_read_b128 v[200:203], v195 offset:384
	ds_read_b128 v[204:207], v195 offset:640
	ds_read_b128 v[208:211], v195 offset:896
	v_pk_mul_f32 v[176:177], v[108:109], v[174:175] op_sel_hi:[1,0]
	v_pk_mul_f32 v[164:165], v[96:97], v[168:169] op_sel_hi:[1,0]
	v_pk_mul_f32 v[180:181], v[100:101], v[170:171] op_sel_hi:[1,0]
	v_pk_mul_f32 v[160:161], v[104:105], v[172:173] op_sel_hi:[1,0]
	v_mov_b32_dpp v96, v164 row_shr:1 row_mask:0xf bank_mask:0xf bound_ctrl:1
	v_mov_b32_dpp v97, v165 row_shr:1 row_mask:0xf bank_mask:0xf bound_ctrl:1
	s_waitcnt lgkmcnt(0)
	v_pk_fma_f32 v[108:109], v[176:177], v[204:205], v[208:209]
	v_pk_mul_f32 v[166:167], v[98:99], v[168:169] op_sel_hi:[1,0]
	v_mov_b32_dpp v98, v180 row_shr:1 row_mask:0xf bank_mask:0xf bound_ctrl:1
	v_mov_b32_dpp v99, v181 row_shr:1 row_mask:0xf bank_mask:0xf bound_ctrl:1
	v_pk_fma_f32 v[108:109], v[200:201], v[96:97], v[108:109]
	v_pk_mul_f32 v[178:179], v[110:111], v[174:175] op_sel_hi:[1,0]
	v_pk_fma_f32 v[98:99], v[196:197], v[98:99], v[108:109]
	v_pk_fma_f32 v[108:109], v[160:161], v[204:205], v[208:209]
	v_pk_mul_f32 v[182:183], v[102:103], v[170:171] op_sel_hi:[1,0]
	v_mov_b32_dpp v100, v166 row_shr:1 row_mask:0xf bank_mask:0xf bound_ctrl:1
	v_mov_b32_dpp v101, v167 row_shr:1 row_mask:0xf bank_mask:0xf bound_ctrl:1
	v_pk_fma_f32 v[110:111], v[178:179], v[206:207], v[210:211]
	v_pk_fma_f32 v[108:109], v[176:177], v[200:201], v[108:109]
	v_pk_mul_f32 v[162:163], v[106:107], v[172:173] op_sel_hi:[1,0]
	v_mov_b32_dpp v102, v182 row_shr:1 row_mask:0xf bank_mask:0xf bound_ctrl:1
	v_mov_b32_dpp v103, v183 row_shr:1 row_mask:0xf bank_mask:0xf bound_ctrl:1
	v_pk_fma_f32 v[110:111], v[202:203], v[100:101], v[110:111]
	v_pk_fma_f32 v[96:97], v[196:197], v[96:97], v[108:109]
	v_pk_fma_f32 v[108:109], v[180:181], v[204:205], v[208:209]
	v_pk_fma_f32 v[102:103], v[198:199], v[102:103], v[110:111]
	v_pk_fma_f32 v[110:111], v[162:163], v[206:207], v[210:211]
	v_pk_fma_f32 v[108:109], v[160:161], v[200:201], v[108:109]
	v_pk_fma_f32 v[110:111], v[178:179], v[202:203], v[110:111]
	v_pk_fma_f32 v[108:109], v[176:177], v[196:197], v[108:109]
	v_pk_fma_f32 v[100:101], v[198:199], v[100:101], v[110:111]
	v_pk_mul_f32 v[96:97], v[184:185], v[96:97]
	v_pk_fma_f32 v[110:111], v[182:183], v[206:207], v[210:211]
	v_pk_mul_f32 v[184:185], v[108:109], v[226:227]
	v_pk_fma_f32 v[108:109], v[164:165], v[204:205], v[208:209]
	v_pk_fma_f32 v[204:205], v[166:167], v[206:207], v[210:211]
	v_pk_fma_f32 v[110:111], v[162:163], v[202:203], v[110:111]
	v_pk_fma_f32 v[202:203], v[182:183], v[202:203], v[204:205]
	v_pk_fma_f32 v[108:109], v[180:181], v[200:201], v[108:109]
	v_pk_mul_f32 v[106:107], v[212:213], v[222:223]
	v_pk_fma_f32 v[110:111], v[178:179], v[198:199], v[110:111]
	v_pk_fma_f32 v[108:109], v[160:161], v[196:197], v[108:109]
	v_pk_fma_f32 v[196:197], v[162:163], v[198:199], v[202:203]
	v_pk_mul_f32 v[104:105], v[214:215], v[220:221]
	v_pk_mul_f32 v[102:103], v[218:219], v[102:103]
	v_pk_mul_f32 v[98:99], v[216:217], v[98:99]
	v_pk_mul_f32 v[100:101], v[224:225], v[100:101]
	v_pk_mul_f32 v[110:111], v[110:111], v[228:229]
	v_pk_mul_f32 v[106:107], v[196:197], v[106:107]
	v_pk_mul_f32 v[196:197], v[108:109], v[104:105]
	v_cvt_pk_bf16_f32 v108, v98, v99
	v_cvt_pk_bf16_f32 v109, v102, v103
	v_cvt_pk_bf16_f32 v104, v96, v97
	v_cvt_pk_bf16_f32 v105, v100, v101
	v_cvt_pk_bf16_f32 v100, v184, v185
	v_cvt_pk_bf16_f32 v101, v110, v111
	s_nop 0
	v_cvt_pk_bf16_f32 v96, v196, v197
	v_cvt_pk_bf16_f32 v97, v106, v107
	ds_read_b128 v[196:199], v195 offset:16
	ds_read_b128 v[200:203], v195 offset:272
	ds_read_b128 v[204:207], v195 offset:528
	ds_read_b128 v[208:211], v195 offset:784
	v_pk_mul_f32 v[92:93], v[92:93], v[174:175] op_sel_hi:[1,0]
	v_pk_mul_f32 v[84:85], v[84:85], v[168:169] op_sel_hi:[1,0]
	v_pk_mul_f32 v[88:89], v[88:89], v[170:171] op_sel_hi:[1,0]
	v_pk_mul_f32 v[80:81], v[80:81], v[172:173] op_sel_hi:[1,0]
	v_mov_b32_dpp v98, v84 row_shr:1 row_mask:0xf bank_mask:0xf bound_ctrl:1
	v_mov_b32_dpp v99, v85 row_shr:1 row_mask:0xf bank_mask:0xf bound_ctrl:1
	s_waitcnt lgkmcnt(0)
; #define PG8_LAS __attribute__((address_space(3)))
; __device__ __forceinline__ float row_up1(float v) { return dpp_mov<0x111>(v); }
; __device__ __forceinline__ float siluf_(float x) { return x * __builtin_amdgcn_rcpf(1.0f + __builtin_amdgcn_exp2f(x * -1.4426950408889634f)); }
;     __device__ __forceinline__ void operator()(f32x4 (&acc)[2][2][4][2], const pg8::Unit& u, int wr, int wc, int fr, int fq) const {
;     ...
;                     g[0] = bb + w2 * x0 + w1 * p1 + w0 * p2; g[1] = bb + w2 * x1 + w1 * x0 + w0 * p1;
;                     g[2] = bb + w2 * x2 + w1 * x1 + w0 * x0; g[3] = bb + w2 * x3 + w1 * x2 + w0 * x1;
; #pragma unroll
;                     for (int m = 0; m < 4; ++m)
; #pragma unroll
;                         for (int c = 0; c < 4; ++c) g[m][c] = siluf_(g[m][c]);
;                 }
;                 __builtin_amdgcn_sched_barrier(0);
;                 {   const PG8_LAS unsigned char* wq = wl + 128 + (8 * fq + 4 * n) * 4;
;                     const f32x4 w0 = *(const PG8_LAS f32x4*)(wq), w1 = *(const PG8_LAS f32x4*)(wq + 256), w2 = *(const PG8_LAS f32x4*)(wq + 512), bb = *(const PG8_LAS f32x4*)(wq + 768);
;                     const f32x4 x0 = acc[ai][1][0][n] * rstd[0], x1 = acc[ai][1][1][n] * rstd[1], x2 = acc[ai][1][2][n] * rstd[2], x3 = acc[ai][1][3][n] * rstd[3];
;                     acc[ai][1][0][n] = x0; acc[ai][1][1][n] = x1; acc[ai][1][2][n] = x2; acc[ai][1][3][n] = x3;
;                     f32x4 p1, p2;
; #pragma unroll
;                     for (int c = 0; c < 4; ++c) { p1[c] = row_up1(x3[c]); p2[c] = row_up1(x2[c]); }
;                     g[0] *= bb + w2 * x0 + w1 * p1 + w0 * p2; g[1] *= bb + w2 * x1 + w1 * x0 + w0 * p1;
	v_pk_fma_f32 v[212:213], v[92:93], v[204:205], v[208:209]
	v_mov_b32_dpp v102, v88 row_shr:1 row_mask:0xf bank_mask:0xf bound_ctrl:1
	v_mov_b32_dpp v103, v89 row_shr:1 row_mask:0xf bank_mask:0xf bound_ctrl:1
	v_pk_fma_f32 v[212:213], v[200:201], v[98:99], v[212:213]
	v_pk_mul_f32 v[94:95], v[94:95], v[174:175] op_sel_hi:[1,0]
	v_pk_fma_f32 v[102:103], v[196:197], v[102:103], v[212:213]
	v_pk_mul_f32 v[86:87], v[86:87], v[168:169] op_sel_hi:[1,0]
	v_exp_f32_e32 v246, v102
	v_pk_fma_f32 v[212:213], v[80:81], v[204:205], v[208:209]
	v_exp_f32_e32 v247, v103
	v_pk_mul_f32 v[90:91], v[90:91], v[170:171] op_sel_hi:[1,0]
	v_mov_b32_dpp v106, v86 row_shr:1 row_mask:0xf bank_mask:0xf bound_ctrl:1
	v_mov_b32_dpp v107, v87 row_shr:1 row_mask:0xf bank_mask:0xf bound_ctrl:1
	v_pk_fma_f32 v[184:185], v[94:95], v[206:207], v[210:211]
	v_pk_fma_f32 v[212:213], v[92:93], v[200:201], v[212:213]
	v_mov_b32_dpp v110, v90 row_shr:1 row_mask:0xf bank_mask:0xf bound_ctrl:1
	v_mov_b32_dpp v111, v91 row_shr:1 row_mask:0xf bank_mask:0xf bound_ctrl:1
	v_pk_fma_f32 v[184:185], v[202:203], v[106:107], v[184:185]
	v_pk_fma_f32 v[98:99], v[196:197], v[98:99], v[212:213]
	v_pk_fma_f32 v[212:213], v[88:89], v[204:205], v[208:209]
	v_pk_fma_f32 v[204:205], v[84:85], v[204:205], v[208:209]
	v_pk_fma_f32 v[110:111], v[198:199], v[110:111], v[184:185]
	v_pk_fma_f32 v[212:213], v[80:81], v[200:201], v[212:213]
	v_pk_fma_f32 v[200:201], v[88:89], v[200:201], v[204:205]
	v_pk_fma_f32 v[212:213], v[92:93], v[196:197], v[212:213]
	v_pk_fma_f32 v[216:217], v[80:81], v[196:197], v[200:201]
	v_pk_add_f32 v[246:247], v[246:247], v[250:251]
	v_rcp_f32_e32 v196, v246
	v_pk_mul_f32 v[82:83], v[82:83], v[172:173] op_sel_hi:[1,0]
	v_exp_f32_e32 v248, v110
	v_pk_fma_f32 v[184:185], v[82:83], v[206:207], v[210:211]
	v_exp_f32_e32 v249, v111
	v_pk_fma_f32 v[184:185], v[94:95], v[202:203], v[184:185]
	v_rcp_f32_e32 v197, v247
	v_pk_fma_f32 v[106:107], v[198:199], v[106:107], v[184:185]
	v_pk_fma_f32 v[184:185], v[90:91], v[206:207], v[210:211]
	v_pk_fma_f32 v[206:207], v[86:87], v[206:207], v[210:211]
	v_pk_fma_f32 v[184:185], v[82:83], v[202:203], v[184:185]
	v_pk_fma_f32 v[202:203], v[90:91], v[202:203], v[206:207]
	v_pk_fma_f32 v[184:185], v[94:95], v[198:199], v[184:185]
	v_pk_fma_f32 v[214:215], v[82:83], v[198:199], v[202:203]
	v_pk_add_f32 v[248:249], v[248:249], v[250:251]
	v_rcp_f32_e32 v198, v248
	v_rcp_f32_e32 v199, v249
	v_exp_f32_e32 v240, v98
	v_exp_f32_e32 v241, v99
	v_pk_mul_f32 v[102:103], v[102:103], v[196:197]
	v_pk_add_f32 v[240:241], v[240:241], v[250:251]
	v_rcp_f32_e32 v196, v240
	v_exp_f32_e32 v242, v106
	v_exp_f32_e32 v243, v107
	v_rcp_f32_e32 v197, v241
	v_pk_mul_f32 v[110:111], v[110:111], v[198:199]
	v_pk_add_f32 v[242:243], v[242:243], v[250:251]
	v_rcp_f32_e32 v198, v242
	v_rcp_f32_e32 v199, v243
	v_exp_f32_e32 v244, v212
	v_exp_f32_e32 v245, v213
	v_pk_mul_f32 v[98:99], v[98:99], v[196:197]
	v_pk_add_f32 v[244:245], v[244:245], v[250:251]
	v_rcp_f32_e32 v196, v244
	v_exp_f32_e32 v246, v184
	v_exp_f32_e32 v247, v185
	v_rcp_f32_e32 v197, v245
	v_pk_add_f32 v[246:247], v[246:247], v[250:251]
	v_rcp_f32_e32 v200, v246
	v_exp_f32_e32 v248, v216
	v_exp_f32_e32 v249, v217
	v_rcp_f32_e32 v201, v247
	v_pk_add_f32 v[248:249], v[248:249], v[250:251]
	v_rcp_f32_e32 v218, v248
	v_exp_f32_e32 v240, v214
	v_exp_f32_e32 v241, v215
	v_rcp_f32_e32 v219, v249
	v_pk_add_f32 v[240:241], v[240:241], v[250:251]
	v_rcp_f32_e32 v220, v240
	v_pk_mul_f32 v[106:107], v[106:107], v[198:199]
	v_rcp_f32_e32 v221, v241
	v_pk_mul_f32 v[212:213], v[212:213], v[196:197]
	v_pk_mul_f32 v[222:223], v[184:185], v[200:201]
	ds_read_b128 v[196:199], v195 offset:144
	ds_read_b128 v[200:203], v195 offset:400
	ds_read_b128 v[204:207], v195 offset:656
	ds_read_b128 v[208:211], v195 offset:912
	v_pk_mul_f32 v[184:185], v[66:67], v[174:175] op_sel_hi:[1,0]
	v_pk_mul_f32 v[174:175], v[64:65], v[174:175] op_sel_hi:[1,0]
	v_pk_mul_f32 v[66:67], v[68:69], v[172:173] op_sel_hi:[1,0]
	v_pk_mul_f32 v[68:69], v[76:77], v[168:169] op_sel_hi:[1,0]
	v_pk_mul_f32 v[70:71], v[70:71], v[172:173] op_sel_hi:[1,0]
	v_pk_mul_f32 v[172:173], v[74:75], v[170:171] op_sel_hi:[1,0]
	v_pk_mul_f32 v[74:75], v[72:73], v[170:171] op_sel_hi:[1,0]
	v_mov_b32_dpp v64, v68 row_shr:1 row_mask:0xf bank_mask:0xf bound_ctrl:1
	v_mov_b32_dpp v65, v69 row_shr:1 row_mask:0xf bank_mask:0xf bound_ctrl:1
	v_pk_mul_f32 v[216:217], v[216:217], v[218:219]
	s_waitcnt lgkmcnt(0)
; __device__ __forceinline__ unsigned pk2(float a, float b) { return pg8::cvt_pk_bf16(a, b); }
;     __device__ __forceinline__ void operator()(f32x4 (&acc)[2][2][4][2], const pg8::Unit& u, int wr, int wc, int fr, int fq) const {
;     ...
;                     g[0] *= bb + w2 * x0 + w1 * p1 + w0 * p2; g[1] *= bb + w2 * x1 + w1 * x0 + w0 * p1;
;                     g[2] *= bb + w2 * x2 + w1 * x1 + w0 * x0; g[3] *= bb + w2 * x3 + w1 * x2 + w0 * x1;
;                 }
; #pragma unroll
;                 for (int m = 0; m < 4; ++m) { pk[n][m].x = pk2(g[m][0], g[m][1]); pk[n][m].y = pk2(g[m][2], g[m][3]); }
;                 __builtin_amdgcn_sched_barrier(0);
;             }
; #pragma unroll
;             for (int m = 0; m < 4; ++m) if (fr != 0 || m >= 2) {
;                 u32x4 w; w.x = pk[0][m].x; w.y = pk[0][m].y; w.z = pk[1][m].x; w.w = pk[1][m].y;
;                 *(u32x4*)(ACT + (size_t)(tb + m) * DFF + colj) = w; }
	v_pk_fma_f32 v[218:219], v[174:175], v[204:205], v[208:209]
	v_pk_mul_f32 v[72:73], v[78:79], v[168:169] op_sel_hi:[1,0]
	v_mov_b32_dpp v76, v74 row_shr:1 row_mask:0xf bank_mask:0xf bound_ctrl:1
	v_mov_b32_dpp v77, v75 row_shr:1 row_mask:0xf bank_mask:0xf bound_ctrl:1
	v_pk_fma_f32 v[218:219], v[200:201], v[64:65], v[218:219]
	v_mov_b32_dpp v78, v72 row_shr:1 row_mask:0xf bank_mask:0xf bound_ctrl:1
	v_mov_b32_dpp v79, v73 row_shr:1 row_mask:0xf bank_mask:0xf bound_ctrl:1
	v_pk_mul_f32 v[214:215], v[214:215], v[220:221]
	v_pk_fma_f32 v[220:221], v[184:185], v[206:207], v[210:211]
	v_pk_fma_f32 v[76:77], v[196:197], v[76:77], v[218:219]
	v_mov_b32_dpp v224, v172 row_shr:1 row_mask:0xf bank_mask:0xf bound_ctrl:1
	v_mov_b32_dpp v225, v173 row_shr:1 row_mask:0xf bank_mask:0xf bound_ctrl:1
	v_pk_fma_f32 v[220:221], v[202:203], v[78:79], v[220:221]
	v_pk_mul_f32 v[76:77], v[102:103], v[76:77]
	v_pk_fma_f32 v[102:103], v[66:67], v[204:205], v[208:209]
	v_pk_fma_f32 v[218:219], v[198:199], v[224:225], v[220:221]
	v_pk_fma_f32 v[102:103], v[174:175], v[200:201], v[102:103]
	v_pk_mul_f32 v[218:219], v[110:111], v[218:219]
	v_pk_fma_f32 v[110:111], v[70:71], v[206:207], v[210:211]
	v_pk_fma_f32 v[64:65], v[196:197], v[64:65], v[102:103]
	v_pk_fma_f32 v[102:103], v[172:173], v[206:207], v[210:211]
	v_pk_fma_f32 v[110:111], v[184:185], v[202:203], v[110:111]
	v_pk_fma_f32 v[102:103], v[70:71], v[202:203], v[102:103]
	v_pk_fma_f32 v[78:79], v[198:199], v[78:79], v[110:111]
	v_pk_mul_f32 v[64:65], v[98:99], v[64:65]
	v_pk_fma_f32 v[98:99], v[74:75], v[204:205], v[208:209]
	v_pk_fma_f32 v[102:103], v[184:185], v[198:199], v[102:103]
	v_pk_mul_f32 v[78:79], v[106:107], v[78:79]
	v_pk_fma_f32 v[98:99], v[66:67], v[200:201], v[98:99]
	v_pk_mul_f32 v[220:221], v[222:223], v[102:103]
	v_pk_fma_f32 v[102:103], v[68:69], v[204:205], v[208:209]
	v_pk_fma_f32 v[106:107], v[72:73], v[206:207], v[210:211]
	v_pk_fma_f32 v[98:99], v[174:175], v[196:197], v[98:99]
	v_pk_fma_f32 v[106:107], v[172:173], v[202:203], v[106:107]
	v_pk_fma_f32 v[102:103], v[74:75], v[200:201], v[102:103]
	v_pk_mul_f32 v[98:99], v[212:213], v[98:99]
	v_pk_fma_f32 v[102:103], v[66:67], v[196:197], v[102:103]
	v_pk_fma_f32 v[106:107], v[70:71], v[198:199], v[106:107]
	v_pk_mul_f32 v[198:199], v[216:217], v[102:103]
	v_pk_mul_f32 v[196:197], v[214:215], v[106:107]
	v_cvt_pk_bf16_f32 v110, v76, v77
	v_cvt_pk_bf16_f32 v111, v218, v219
	v_cvt_pk_bf16_f32 v106, v64, v65
	v_cvt_pk_bf16_f32 v107, v78, v79
	v_cvt_pk_bf16_f32 v102, v98, v99
	v_cvt_pk_bf16_f32 v103, v220, v221
	v_cvt_pk_bf16_f32 v98, v198, v199
	s_nop 0
	v_cvt_pk_bf16_f32 v99, v196, v197
	v_lshlrev_b64 v[64:65], 1, v[158:159]
	s_and_saveexec_b64 s[8:9], s[0:1]
	s_cbranch_execz .LBB0_750
	v_mov_b64_e32 v[76:77], s[22:23]
	v_mad_i64_i32 v[78:79], s[10:11], v148, s56, v[76:77]
	v_mad_i64_i32 v[76:77], s[10:11], v150, s56, v[76:77]
	v_lshl_add_u64 v[78:79], v[78:79], 0, v[64:65]
	v_lshl_add_u64 v[76:77], v[76:77], 0, v[64:65]
	global_store_dwordx4 v[78:79], v[108:111], off
	global_store_dwordx4 v[76:77], v[104:107], off

; #define PG8_LAS __attribute__((address_space(3)))
; __device__ __forceinline__ float row_up1(float v) { return dpp_mov<0x111>(v); }
; __device__ __forceinline__ float siluf_(float x) { return x * __builtin_amdgcn_rcpf(1.0f + __builtin_amdgcn_exp2f(x * -1.4426950408889634f)); }
;     __device__ __forceinline__ void operator()(f32x4 (&acc)[2][2][4][2], const pg8::Unit& u, int wr, int wc, int fr, int fq) const {
;     ...
;         for (int ai = 0; ai < 2; ++ai) {
;             const int tb = u.pm * 256 + ai * 128 + wr * 64 + 4 * fr;
;             float rstd[4];
; #pragma unroll
;             for (int m = 0; m < 4; ++m) { const f32x4 sv = *(const f32x4*)(SS + (size_t)(tb + m) * 16 + 4 * fq); float s = (sv[0] + sv[1]) + (sv[2] + sv[3]); s += __shfl_xor(s, 16); s += __shfl_xor(s, 32);
;                 rstd[m] = rsqrtf(s * (1.0f / 1024.0f) + EPS); }
;             u32x2 pk[2][4];
; #pragma unroll
;             for (int n = 0; n < 2; ++n) {
;                 f32x4 g[4];
;                 {   const PG8_LAS unsigned char* wq = wl + (8 * fq + 4 * n) * 4;
;                     const f32x4 w0 = *(const PG8_LAS f32x4*)(wq), w1 = *(const PG8_LAS f32x4*)(wq + 256), w2 = *(const PG8_LAS f32x4*)(wq + 512), bb = *(const PG8_LAS f32x4*)(wq + 768);
;                     const f32x4 x0 = acc[ai][0][0][n] * rstd[0], x1 = acc[ai][0][1][n] * rstd[1], x2 = acc[ai][0][2][n] * rstd[2], x3 = acc[ai][0][3][n] * rstd[3];
;                     acc[ai][0][0][n] = x0; acc[ai][0][1][n] = x1; acc[ai][0][2][n] = x2; acc[ai][0][3][n] = x3;
;                     f32x4 p1, p2;
; #pragma unroll
;                     for (int c = 0; c < 4; ++c) { p1[c] = row_up1(x3[c]); p2[c] = row_up1(x2[c]); }
;                     g[0] = bb + w2 * x0 + w1 * p1 + w0 * p2; g[1] = bb + w2 * x1 + w1 * x0 + w0 * p1;
;                     g[2] = bb + w2 * x2 + w1 * x1 + w0 * x0; g[3] = bb + w2 * x3 + w1 * x2 + w0 * x1;
; #pragma unroll
;                     for (int m = 0; m < 4; ++m)
; #pragma unroll
;                         for (int c = 0; c < 4; ++c) g[m][c] = siluf_(g[m][c]);
.LBB0_754:
	s_or_b64 exec, exec, s[8:9]
	s_nop 0
	v_add_u32_e32 v66, 0x80, v148
	v_ashrrev_i32_e32 v67, 31, v66
	v_lshlrev_b64 v[68:69], 6, v[66:67]
	v_lshl_add_u64 v[246:247], v[138:139], 0, v[68:69]
	v_add_u32_e32 v68, 0x81, v148
	global_load_dwordx4 v[74:77], v[246:247], off
	global_load_dwordx4 v[78:81], v[246:247], off offset:64
	v_add_u32_e32 v70, 0x82, v148
	global_load_dwordx4 v[82:85], v[246:247], off offset:128
	v_add_u32_e32 v72, 0x83, v148
	global_load_dwordx4 v[86:89], v[246:247], off offset:192
	s_waitcnt vmcnt(3)
	v_mov_b32_e32 v90, v75
	v_mov_b32_e32 v91, v76
	v_mov_b32_e32 v75, v77
	s_waitcnt vmcnt(2)
	v_mov_b32_e32 v76, v79
	v_mov_b32_e32 v77, v80
	v_mov_b32_e32 v79, v81
	s_waitcnt vmcnt(1)
	v_mov_b32_e32 v80, v83
	v_mov_b32_e32 v81, v84
	v_mov_b32_e32 v83, v85
	v_pk_add_f32 v[74:75], v[90:91], v[74:75]
	v_pk_add_f32 v[76:77], v[76:77], v[78:79]
	s_waitcnt vmcnt(0)
	v_mov_b32_e32 v84, v87
	v_mov_b32_e32 v85, v88
	v_mov_b32_e32 v87, v89
	v_pk_add_f32 v[78:79], v[80:81], v[82:83]
	v_pk_add_f32 v[80:81], v[84:85], v[86:87]
	v_mov_b32_e32 v82, v76
	v_mov_b32_e32 v83, v74
	v_mov_b32_e32 v74, v77
	v_mov_b32_e32 v76, v80
	v_mov_b32_e32 v77, v78
	v_mov_b32_e32 v78, v81
	v_pk_add_f32 v[74:75], v[82:83], v[74:75]
	v_pk_add_f32 v[76:77], v[76:77], v[78:79]
	ds_bpermute_b32 v79, v149, v75
	ds_bpermute_b32 v78, v149, v74
	ds_bpermute_b32 v81, v149, v77
	ds_bpermute_b32 v80, v149, v76
	v_mov_b64_e32 v[82:83], s[38:39]
	s_waitcnt lgkmcnt(2)
	v_pk_add_f32 v[84:85], v[74:75], v[78:79]
	ds_bpermute_b32 v89, v151, v85
	s_waitcnt lgkmcnt(1)
	v_pk_add_f32 v[86:87], v[76:77], v[80:81]
	ds_bpermute_b32 v88, v151, v84
	ds_bpermute_b32 v99, v151, v87
	ds_bpermute_b32 v98, v151, v86
	ds_read_b128 v[74:77], v195
	ds_read_b128 v[78:81], v195 offset:256
	ds_read_b128 v[90:93], v195 offset:512
	ds_read_b128 v[94:97], v195 offset:768
	s_waitcnt lgkmcnt(6)
	v_pk_add_f32 v[84:85], v[84:85], v[88:89]
	s_nop 0
	v_pk_fma_f32 v[84:85], v[84:85], s[24:25], v[82:83] op_sel_hi:[1,0,0]
	s_waitcnt lgkmcnt(4)
	v_pk_add_f32 v[86:87], v[86:87], v[98:99]
	v_pk_fma_f32 v[82:83], v[86:87], s[24:25], v[82:83] op_sel_hi:[1,0,0]
	v_rsq_f32_e32 v67, v85
	v_rsq_f32_e32 v73, v82
	v_rsq_f32_e32 v69, v84
	v_rsq_f32_e32 v71, v83
	v_mov_b32_e32 v88, v67
	v_mov_b32_e32 v82, v73
	v_mov_b32_e32 v84, v71
	v_pk_mul_f32 v[60:61], v[60:61], v[88:89] op_sel_hi:[1,0]
	v_pk_mul_f32 v[48:49], v[48:49], v[82:83] op_sel_hi:[1,0]
	v_pk_mul_f32 v[52:53], v[52:53], v[84:85] op_sel_hi:[1,0]
	s_waitcnt lgkmcnt(0)
	v_pk_fma_f32 v[108:109], v[90:91], v[60:61], v[94:95]
	v_mov_b32_dpp v98, v48 row_shr:1 row_mask:0xf bank_mask:0xf bound_ctrl:1
	v_mov_b32_dpp v99, v49 row_shr:1 row_mask:0xf bank_mask:0xf bound_ctrl:1
	v_mov_b32_dpp v100, v52 row_shr:1 row_mask:0xf bank_mask:0xf bound_ctrl:1
	v_mov_b32_dpp v101, v53 row_shr:1 row_mask:0xf bank_mask:0xf bound_ctrl:1
	v_pk_fma_f32 v[108:109], v[78:79], v[98:99], v[108:109]
	v_mov_b32_e32 v86, v69
	v_pk_fma_f32 v[100:101], v[74:75], v[100:101], v[108:109]
	v_pk_mul_f32 v[62:63], v[62:63], v[88:89] op_sel_hi:[1,0]
	v_exp_f32_e32 v242, v100
	v_pk_mul_f32 v[50:51], v[50:51], v[82:83] op_sel_hi:[1,0]
	v_exp_f32_e32 v243, v101
	v_pk_mul_f32 v[56:57], v[56:57], v[86:87] op_sel_hi:[1,0]
	v_pk_mul_f32 v[54:55], v[54:55], v[84:85] op_sel_hi:[1,0]
	v_mov_b32_dpp v102, v50 row_shr:1 row_mask:0xf bank_mask:0xf bound_ctrl:1
	v_mov_b32_dpp v103, v51 row_shr:1 row_mask:0xf bank_mask:0xf bound_ctrl:1
	v_pk_fma_f32 v[106:107], v[92:93], v[62:63], v[96:97]
	v_mov_b32_dpp v104, v54 row_shr:1 row_mask:0xf bank_mask:0xf bound_ctrl:1
	v_mov_b32_dpp v105, v55 row_shr:1 row_mask:0xf bank_mask:0xf bound_ctrl:1
	v_pk_fma_f32 v[112:113], v[90:91], v[56:57], v[94:95]
	v_pk_fma_f32 v[106:107], v[80:81], v[102:103], v[106:107]
	v_pk_fma_f32 v[108:109], v[90:91], v[52:53], v[94:95]
	v_pk_fma_f32 v[90:91], v[90:91], v[48:49], v[94:95]
	v_pk_fma_f32 v[112:113], v[78:79], v[60:61], v[112:113]
	v_pk_fma_f32 v[104:105], v[76:77], v[104:105], v[106:107]
	v_pk_fma_f32 v[108:109], v[78:79], v[56:57], v[108:109]
	v_pk_fma_f32 v[78:79], v[78:79], v[52:53], v[90:91]
	v_pk_fma_f32 v[98:99], v[74:75], v[98:99], v[112:113]
	v_pk_fma_f32 v[108:109], v[74:75], v[60:61], v[108:109]
	v_pk_fma_f32 v[116:117], v[74:75], v[56:57], v[78:79]
	v_pk_add_f32 v[242:243], v[242:243], v[250:251]
	v_rcp_f32_e32 v74, v242
	v_exp_f32_e32 v244, v104
	v_exp_f32_e32 v245, v105
	v_pk_mul_f32 v[58:59], v[58:59], v[86:87] op_sel_hi:[1,0]
	v_pk_fma_f32 v[106:107], v[92:93], v[54:55], v[96:97]
	v_pk_fma_f32 v[110:111], v[92:93], v[58:59], v[96:97]
	v_pk_fma_f32 v[92:93], v[92:93], v[50:51], v[96:97]
	v_pk_fma_f32 v[110:111], v[80:81], v[62:63], v[110:111]
	v_pk_fma_f32 v[106:107], v[80:81], v[58:59], v[106:107]
	v_pk_fma_f32 v[80:81], v[80:81], v[54:55], v[92:93]
	v_rcp_f32_e32 v75, v243
	v_pk_fma_f32 v[102:103], v[76:77], v[102:103], v[110:111]
	v_pk_fma_f32 v[106:107], v[76:77], v[62:63], v[106:107]
	v_pk_fma_f32 v[114:115], v[76:77], v[58:59], v[80:81]
	v_pk_add_f32 v[244:245], v[244:245], v[250:251]
	v_rcp_f32_e32 v76, v244
	v_rcp_f32_e32 v77, v245
	v_exp_f32_e32 v246, v98
	v_exp_f32_e32 v247, v99
	v_pk_mul_f32 v[118:119], v[100:101], v[74:75]
	v_pk_add_f32 v[246:247], v[246:247], v[250:251]
	v_rcp_f32_e32 v74, v246
	v_exp_f32_e32 v248, v102
	v_exp_f32_e32 v249, v103
	v_rcp_f32_e32 v75, v247
	v_pk_mul_f32 v[120:121], v[104:105], v[76:77]
	v_pk_add_f32 v[248:249], v[248:249], v[250:251]
	v_rcp_f32_e32 v76, v248
	v_rcp_f32_e32 v77, v249
	v_exp_f32_e32 v240, v108
	v_exp_f32_e32 v241, v109
	v_pk_mul_f32 v[122:123], v[98:99], v[74:75]
	v_pk_add_f32 v[240:241], v[240:241], v[250:251]
	v_rcp_f32_e32 v74, v240
	v_exp_f32_e32 v242, v106
	v_exp_f32_e32 v243, v107
	v_rcp_f32_e32 v75, v241
	v_pk_add_f32 v[242:243], v[242:243], v[250:251]
	v_rcp_f32_e32 v78, v242
	v_exp_f32_e32 v244, v116
	v_exp_f32_e32 v245, v117
	v_rcp_f32_e32 v79, v243
	v_pk_add_f32 v[244:245], v[244:245], v[250:251]
	v_rcp_f32_e32 v124, v244
	v_exp_f32_e32 v246, v114
	v_exp_f32_e32 v247, v115
	v_rcp_f32_e32 v125, v245
	v_pk_add_f32 v[246:247], v[246:247], v[250:251]
	v_rcp_f32_e32 v126, v246
	v_rcp_f32_e32 v127, v247
	v_pk_mul_f32 v[148:149], v[102:103], v[76:77]
	v_pk_mul_f32 v[150:151], v[108:109], v[74:75]
	v_pk_mul_f32 v[154:155], v[106:107], v[78:79]
	ds_read_b128 v[98:101], v195 offset:128
	ds_read_b128 v[102:105], v195 offset:384
	ds_read_b128 v[106:109], v195 offset:640
	ds_read_b128 v[110:113], v195 offset:896
	v_pk_mul_f32 v[90:91], v[44:45], v[88:89] op_sel_hi:[1,0]
	v_pk_mul_f32 v[78:79], v[32:33], v[82:83] op_sel_hi:[1,0]
	v_pk_mul_f32 v[94:95], v[36:37], v[84:85] op_sel_hi:[1,0]
	v_pk_mul_f32 v[74:75], v[40:41], v[86:87] op_sel_hi:[1,0]
	v_mov_b32_dpp v32, v78 row_shr:1 row_mask:0xf bank_mask:0xf bound_ctrl:1
	v_mov_b32_dpp v33, v79 row_shr:1 row_mask:0xf bank_mask:0xf bound_ctrl:1
	s_waitcnt lgkmcnt(0)
; #define PG8_LAS __attribute__((address_space(3)))
; __device__ __forceinline__ unsigned pk2(float a, float b) { return pg8::cvt_pk_bf16(a, b); }
; __device__ __forceinline__ float row_up1(float v) { return dpp_mov<0x111>(v); }
;     __device__ __forceinline__ void operator()(f32x4 (&acc)[2][2][4][2], const pg8::Unit& u, int wr, int wc, int fr, int fq) const {
;     ...
;                 {   const PG8_LAS unsigned char* wq = wl + 128 + (8 * fq + 4 * n) * 4;
;                     const f32x4 w0 = *(const PG8_LAS f32x4*)(wq), w1 = *(const PG8_LAS f32x4*)(wq + 256), w2 = *(const PG8_LAS f32x4*)(wq + 512), bb = *(const PG8_LAS f32x4*)(wq + 768);
;                     const f32x4 x0 = acc[ai][1][0][n] * rstd[0], x1 = acc[ai][1][1][n] * rstd[1], x2 = acc[ai][1][2][n] * rstd[2], x3 = acc[ai][1][3][n] * rstd[3];
;                     acc[ai][1][0][n] = x0; acc[ai][1][1][n] = x1; acc[ai][1][2][n] = x2; acc[ai][1][3][n] = x3;
;                     f32x4 p1, p2;
; #pragma unroll
;                     for (int c = 0; c < 4; ++c) { p1[c] = row_up1(x3[c]); p2[c] = row_up1(x2[c]); }
;                     g[0] *= bb + w2 * x0 + w1 * p1 + w0 * p2; g[1] *= bb + w2 * x1 + w1 * x0 + w0 * p1;
;                     g[2] *= bb + w2 * x2 + w1 * x1 + w0 * x0; g[3] *= bb + w2 * x3 + w1 * x2 + w0 * x1;
;                 }
; #pragma unroll
;                 for (int m = 0; m < 4; ++m) { pk[n][m].x = pk2(g[m][0], g[m][1]); pk[n][m].y = pk2(g[m][2], g[m][3]); }
	v_pk_fma_f32 v[44:45], v[90:91], v[106:107], v[110:111]
	v_pk_mul_f32 v[80:81], v[34:35], v[82:83] op_sel_hi:[1,0]
	v_mov_b32_dpp v34, v94 row_shr:1 row_mask:0xf bank_mask:0xf bound_ctrl:1
	v_mov_b32_dpp v35, v95 row_shr:1 row_mask:0xf bank_mask:0xf bound_ctrl:1
	v_pk_fma_f32 v[44:45], v[102:103], v[32:33], v[44:45]
	v_pk_mul_f32 v[92:93], v[46:47], v[88:89] op_sel_hi:[1,0]
	v_pk_fma_f32 v[34:35], v[98:99], v[34:35], v[44:45]
	v_pk_fma_f32 v[44:45], v[74:75], v[106:107], v[110:111]
	v_pk_mul_f32 v[96:97], v[38:39], v[84:85] op_sel_hi:[1,0]
	v_mov_b32_dpp v36, v80 row_shr:1 row_mask:0xf bank_mask:0xf bound_ctrl:1
	v_mov_b32_dpp v37, v81 row_shr:1 row_mask:0xf bank_mask:0xf bound_ctrl:1
	v_pk_fma_f32 v[46:47], v[92:93], v[108:109], v[112:113]
	v_pk_fma_f32 v[44:45], v[90:91], v[102:103], v[44:45]
	v_pk_mul_f32 v[76:77], v[42:43], v[86:87] op_sel_hi:[1,0]
	v_mov_b32_dpp v38, v96 row_shr:1 row_mask:0xf bank_mask:0xf bound_ctrl:1
	v_mov_b32_dpp v39, v97 row_shr:1 row_mask:0xf bank_mask:0xf bound_ctrl:1
	v_pk_fma_f32 v[46:47], v[104:105], v[36:37], v[46:47]
	v_pk_fma_f32 v[32:33], v[98:99], v[32:33], v[44:45]
	v_pk_fma_f32 v[44:45], v[94:95], v[106:107], v[110:111]
	v_pk_fma_f32 v[38:39], v[100:101], v[38:39], v[46:47]
	v_pk_fma_f32 v[46:47], v[76:77], v[108:109], v[112:113]
	v_pk_fma_f32 v[44:45], v[74:75], v[102:103], v[44:45]
	v_pk_fma_f32 v[46:47], v[92:93], v[104:105], v[46:47]
	v_pk_fma_f32 v[44:45], v[90:91], v[98:99], v[44:45]
	v_pk_mul_f32 v[42:43], v[114:115], v[126:127]
	v_pk_fma_f32 v[36:37], v[100:101], v[36:37], v[46:47]
	v_pk_fma_f32 v[46:47], v[96:97], v[108:109], v[112:113]
	v_pk_mul_f32 v[114:115], v[44:45], v[150:151]
	v_pk_fma_f32 v[44:45], v[78:79], v[106:107], v[110:111]
	v_pk_fma_f32 v[106:107], v[80:81], v[108:109], v[112:113]
	v_pk_fma_f32 v[46:47], v[76:77], v[104:105], v[46:47]
	v_pk_fma_f32 v[104:105], v[96:97], v[104:105], v[106:107]
	v_pk_fma_f32 v[44:45], v[94:95], v[102:103], v[44:45]
	v_pk_mul_f32 v[40:41], v[116:117], v[124:125]
	v_pk_fma_f32 v[46:47], v[92:93], v[100:101], v[46:47]
	v_pk_fma_f32 v[44:45], v[74:75], v[98:99], v[44:45]
	v_pk_fma_f32 v[98:99], v[76:77], v[100:101], v[104:105]
	v_pk_mul_f32 v[38:39], v[120:121], v[38:39]
	v_pk_mul_f32 v[34:35], v[118:119], v[34:35]
	v_pk_mul_f32 v[36:37], v[148:149], v[36:37]
	v_pk_mul_f32 v[32:33], v[122:123], v[32:33]
	v_pk_mul_f32 v[46:47], v[46:47], v[154:155]
	v_pk_mul_f32 v[42:43], v[98:99], v[42:43]
	v_pk_mul_f32 v[98:99], v[44:45], v[40:41]
	v_cvt_pk_bf16_f32 v44, v34, v35
	v_cvt_pk_bf16_f32 v45, v38, v39
	v_cvt_pk_bf16_f32 v40, v32, v33
	v_cvt_pk_bf16_f32 v41, v36, v37
	v_cvt_pk_bf16_f32 v36, v114, v115
	v_cvt_pk_bf16_f32 v37, v46, v47
	s_nop 0
	v_cvt_pk_bf16_f32 v32, v98, v99
	v_cvt_pk_bf16_f32 v33, v42, v43
	ds_read_b128 v[102:105], v195 offset:16
	ds_read_b128 v[106:109], v195 offset:272
	ds_read_b128 v[110:113], v195 offset:528
	ds_read_b128 v[114:117], v195 offset:784
	v_pk_mul_f32 v[98:99], v[16:17], v[88:89] op_sel_hi:[1,0]
	v_pk_mul_f32 v[16:17], v[20:21], v[86:87] op_sel_hi:[1,0]
	v_pk_mul_f32 v[20:21], v[28:29], v[82:83] op_sel_hi:[1,0]
	v_pk_mul_f32 v[24:25], v[24:25], v[84:85] op_sel_hi:[1,0]
	s_waitcnt lgkmcnt(0)
	v_pk_fma_f32 v[46:47], v[98:99], v[110:111], v[114:115]
	v_mov_b32_dpp v28, v20 row_shr:1 row_mask:0xf bank_mask:0xf bound_ctrl:1
	v_mov_b32_dpp v29, v21 row_shr:1 row_mask:0xf bank_mask:0xf bound_ctrl:1
	v_pk_mul_f32 v[100:101], v[18:19], v[88:89] op_sel_hi:[1,0]
	v_pk_mul_f32 v[18:19], v[22:23], v[86:87] op_sel_hi:[1,0]
	v_pk_mul_f32 v[22:23], v[30:31], v[82:83] op_sel_hi:[1,0]
	v_mov_b32_dpp v30, v24 row_shr:1 row_mask:0xf bank_mask:0xf bound_ctrl:1
	v_mov_b32_dpp v31, v25 row_shr:1 row_mask:0xf bank_mask:0xf bound_ctrl:1
	v_pk_fma_f32 v[46:47], v[106:107], v[28:29], v[46:47]
	v_pk_mul_f32 v[26:27], v[26:27], v[84:85] op_sel_hi:[1,0]
	v_pk_fma_f32 v[30:31], v[102:103], v[30:31], v[46:47]
	v_pk_fma_f32 v[46:47], v[16:17], v[110:111], v[114:115]
	v_exp_f32_e32 v248, v30
	v_exp_f32_e32 v249, v31
	v_mov_b32_dpp v34, v22 row_shr:1 row_mask:0xf bank_mask:0xf bound_ctrl:1
	v_mov_b32_dpp v35, v23 row_shr:1 row_mask:0xf bank_mask:0xf bound_ctrl:1
	v_pk_fma_f32 v[42:43], v[100:101], v[112:113], v[116:117]
	v_pk_fma_f32 v[46:47], v[98:99], v[106:107], v[46:47]
	v_mov_b32_dpp v38, v26 row_shr:1 row_mask:0xf bank_mask:0xf bound_ctrl:1
	v_mov_b32_dpp v39, v27 row_shr:1 row_mask:0xf bank_mask:0xf bound_ctrl:1
	v_pk_fma_f32 v[42:43], v[108:109], v[34:35], v[42:43]
	v_pk_fma_f32 v[28:29], v[102:103], v[28:29], v[46:47]
	v_pk_fma_f32 v[46:47], v[24:25], v[110:111], v[114:115]
	v_pk_fma_f32 v[110:111], v[20:21], v[110:111], v[114:115]
	v_pk_fma_f32 v[38:39], v[104:105], v[38:39], v[42:43]
	v_pk_fma_f32 v[46:47], v[16:17], v[106:107], v[46:47]
	v_pk_fma_f32 v[106:107], v[24:25], v[106:107], v[110:111]
	v_pk_fma_f32 v[46:47], v[98:99], v[102:103], v[46:47]
	v_pk_fma_f32 v[120:121], v[16:17], v[102:103], v[106:107]
	v_pk_add_f32 v[248:249], v[248:249], v[250:251]
	v_rcp_f32_e32 v102, v248
	v_exp_f32_e32 v240, v38
	v_pk_fma_f32 v[42:43], v[18:19], v[112:113], v[116:117]
	v_exp_f32_e32 v241, v39
	v_pk_fma_f32 v[42:43], v[100:101], v[108:109], v[42:43]
	v_rcp_f32_e32 v103, v249
	v_pk_fma_f32 v[34:35], v[104:105], v[34:35], v[42:43]
	v_pk_fma_f32 v[42:43], v[26:27], v[112:113], v[116:117]
; #define PG8_LAS __attribute__((address_space(3)))
; __device__ __forceinline__ unsigned pk2(float a, float b) { return pg8::cvt_pk_bf16(a, b); }
; __device__ __forceinline__ float row_up1(float v) { return dpp_mov<0x111>(v); }
; __device__ __forceinline__ float siluf_(float x) { return x * __builtin_amdgcn_rcpf(1.0f + __builtin_amdgcn_exp2f(x * -1.4426950408889634f)); }
;     __device__ __forceinline__ void operator()(f32x4 (&acc)[2][2][4][2], const pg8::Unit& u, int wr, int wc, int fr, int fq) const {
;     ...
;                     g[0] = bb + w2 * x0 + w1 * p1 + w0 * p2; g[1] = bb + w2 * x1 + w1 * x0 + w0 * p1;
;                     g[2] = bb + w2 * x2 + w1 * x1 + w0 * x0; g[3] = bb + w2 * x3 + w1 * x2 + w0 * x1;
; #pragma unroll
;                     for (int m = 0; m < 4; ++m)
; #pragma unroll
;                         for (int c = 0; c < 4; ++c) g[m][c] = siluf_(g[m][c]);
;                 }
;                 __builtin_amdgcn_sched_barrier(0);
;                 {   const PG8_LAS unsigned char* wq = wl + 128 + (8 * fq + 4 * n) * 4;
;                     const f32x4 w0 = *(const PG8_LAS f32x4*)(wq), w1 = *(const PG8_LAS f32x4*)(wq + 256), w2 = *(const PG8_LAS f32x4*)(wq + 512), bb = *(const PG8_LAS f32x4*)(wq + 768);
;                     const f32x4 x0 = acc[ai][1][0][n] * rstd[0], x1 = acc[ai][1][1][n] * rstd[1], x2 = acc[ai][1][2][n] * rstd[2], x3 = acc[ai][1][3][n] * rstd[3];
;                     acc[ai][1][0][n] = x0; acc[ai][1][1][n] = x1; acc[ai][1][2][n] = x2; acc[ai][1][3][n] = x3;
;                     f32x4 p1, p2;
; #pragma unroll
;                     for (int c = 0; c < 4; ++c) { p1[c] = row_up1(x3[c]); p2[c] = row_up1(x2[c]); }
;                     g[0] *= bb + w2 * x0 + w1 * p1 + w0 * p2; g[1] *= bb + w2 * x1 + w1 * x0 + w0 * p1;
;                     g[2] *= bb + w2 * x2 + w1 * x1 + w0 * x0; g[3] *= bb + w2 * x3 + w1 * x2 + w0 * x1;
;                 }
; #pragma unroll
;                 for (int m = 0; m < 4; ++m) { pk[n][m].x = pk2(g[m][0], g[m][1]); pk[n][m].y = pk2(g[m][2], g[m][3]); }
;                 __builtin_amdgcn_sched_barrier(0);
;             }
; #pragma unroll
;             for (int m = 0; m < 4; ++m) if (fr != 0 || m >= 2) {
;                 u32x4 w; w.x = pk[0][m].x; w.y = pk[0][m].y; w.z = pk[1][m].x; w.w = pk[1][m].y;
;                 *(u32x4*)(ACT + (size_t)(tb + m) * DFF + colj) = w; }
	v_pk_fma_f32 v[112:113], v[22:23], v[112:113], v[116:117]
	v_pk_fma_f32 v[42:43], v[18:19], v[108:109], v[42:43]
	v_pk_fma_f32 v[108:109], v[26:27], v[108:109], v[112:113]
	v_pk_fma_f32 v[42:43], v[100:101], v[104:105], v[42:43]
	v_pk_fma_f32 v[118:119], v[18:19], v[104:105], v[108:109]
	v_pk_add_f32 v[240:241], v[240:241], v[250:251]
	v_rcp_f32_e32 v104, v240
	v_rcp_f32_e32 v105, v241
	v_exp_f32_e32 v242, v34
	v_pk_mul_f32 v[122:123], v[30:31], v[102:103]
	v_exp_f32_e32 v243, v35
	v_exp_f32_e32 v244, v28
	v_exp_f32_e32 v245, v29
	v_pk_add_f32 v[242:243], v[242:243], v[250:251]
	v_rcp_f32_e32 v102, v242
	v_pk_add_f32 v[244:245], v[244:245], v[250:251]
	v_rcp_f32_e32 v103, v243
	v_rcp_f32_e32 v30, v244
	v_rcp_f32_e32 v31, v245
	v_exp_f32_e32 v246, v46
	v_exp_f32_e32 v247, v47
	v_pk_mul_f32 v[124:125], v[28:29], v[30:31]
	v_pk_add_f32 v[246:247], v[246:247], v[250:251]
	v_exp_f32_e32 v248, v120
	v_exp_f32_e32 v249, v121
	v_exp_f32_e32 v240, v42
	v_exp_f32_e32 v241, v43
	v_pk_add_f32 v[248:249], v[248:249], v[250:251]
	v_rcp_f32_e32 v126, v248
	v_pk_add_f32 v[240:241], v[240:241], v[250:251]
	v_exp_f32_e32 v242, v118
	v_rcp_f32_e32 v28, v246
	v_rcp_f32_e32 v29, v247
	v_rcp_f32_e32 v30, v240
	v_rcp_f32_e32 v31, v241
	v_exp_f32_e32 v243, v119
	v_rcp_f32_e32 v127, v249
	v_pk_mul_f32 v[38:39], v[38:39], v[104:105]
	v_pk_add_f32 v[242:243], v[242:243], v[250:251]
	v_rcp_f32_e32 v148, v242
	v_pk_mul_f32 v[34:35], v[34:35], v[102:103]
	v_pk_mul_f32 v[46:47], v[46:47], v[28:29]
	v_pk_mul_f32 v[42:43], v[42:43], v[30:31]
	v_rcp_f32_e32 v149, v243
	ds_read_b128 v[102:105], v195 offset:144
	ds_read_b128 v[106:109], v195 offset:400
	ds_read_b128 v[110:113], v195 offset:656
	ds_read_b128 v[114:117], v195 offset:912
	v_pk_mul_f32 v[30:31], v[2:3], v[88:89] op_sel_hi:[1,0]
	v_pk_mul_f32 v[28:29], v[0:1], v[88:89] op_sel_hi:[1,0]
	v_pk_mul_f32 v[2:3], v[6:7], v[86:87] op_sel_hi:[1,0]
	v_pk_mul_f32 v[0:1], v[4:5], v[86:87] op_sel_hi:[1,0]
	v_pk_mul_f32 v[6:7], v[14:15], v[82:83] op_sel_hi:[1,0]
	v_pk_mul_f32 v[4:5], v[12:13], v[82:83] op_sel_hi:[1,0]
	v_pk_mul_f32 v[10:11], v[10:11], v[84:85] op_sel_hi:[1,0]
	v_pk_mul_f32 v[8:9], v[8:9], v[84:85] op_sel_hi:[1,0]
	v_mov_b32_dpp v12, v4 row_shr:1 row_mask:0xf bank_mask:0xf bound_ctrl:1
	v_mov_b32_dpp v13, v5 row_shr:1 row_mask:0xf bank_mask:0xf bound_ctrl:1
	v_mov_b32_dpp v82, v6 row_shr:1 row_mask:0xf bank_mask:0xf bound_ctrl:1
	v_mov_b32_dpp v83, v7 row_shr:1 row_mask:0xf bank_mask:0xf bound_ctrl:1
	v_pk_mul_f32 v[86:87], v[120:121], v[126:127]
	v_pk_mul_f32 v[88:89], v[118:119], v[148:149]
	s_waitcnt lgkmcnt(0)
	v_pk_fma_f32 v[118:119], v[28:29], v[110:111], v[114:115]
	v_pk_fma_f32 v[120:121], v[30:31], v[112:113], v[116:117]
	v_mov_b32_dpp v14, v8 row_shr:1 row_mask:0xf bank_mask:0xf bound_ctrl:1
	v_mov_b32_dpp v15, v9 row_shr:1 row_mask:0xf bank_mask:0xf bound_ctrl:1
	v_mov_b32_dpp v84, v10 row_shr:1 row_mask:0xf bank_mask:0xf bound_ctrl:1
	v_mov_b32_dpp v85, v11 row_shr:1 row_mask:0xf bank_mask:0xf bound_ctrl:1
	v_pk_fma_f32 v[120:121], v[108:109], v[82:83], v[120:121]
	v_pk_fma_f32 v[118:119], v[106:107], v[12:13], v[118:119]
	v_pk_fma_f32 v[84:85], v[104:105], v[84:85], v[120:121]
	v_pk_fma_f32 v[14:15], v[102:103], v[14:15], v[118:119]
	v_pk_fma_f32 v[118:119], v[2:3], v[112:113], v[116:117]
	v_pk_mul_f32 v[38:39], v[38:39], v[84:85]
	v_pk_fma_f32 v[84:85], v[0:1], v[110:111], v[114:115]
	v_pk_fma_f32 v[118:119], v[30:31], v[108:109], v[118:119]
	v_pk_fma_f32 v[84:85], v[28:29], v[106:107], v[84:85]
	v_pk_fma_f32 v[82:83], v[104:105], v[82:83], v[118:119]
	v_pk_fma_f32 v[12:13], v[102:103], v[12:13], v[84:85]
	v_pk_mul_f32 v[34:35], v[34:35], v[82:83]
	v_pk_fma_f32 v[82:83], v[8:9], v[110:111], v[114:115]
	v_pk_fma_f32 v[84:85], v[10:11], v[112:113], v[116:117]
	v_pk_fma_f32 v[82:83], v[0:1], v[106:107], v[82:83]
	v_pk_fma_f32 v[84:85], v[2:3], v[108:109], v[84:85]
	v_pk_fma_f32 v[82:83], v[28:29], v[102:103], v[82:83]
	v_pk_fma_f32 v[84:85], v[30:31], v[104:105], v[84:85]
	v_pk_mul_f32 v[82:83], v[46:47], v[82:83]
	v_pk_mul_f32 v[84:85], v[42:43], v[84:85]
	v_pk_fma_f32 v[42:43], v[4:5], v[110:111], v[114:115]
	v_pk_fma_f32 v[46:47], v[6:7], v[112:113], v[116:117]
	v_pk_fma_f32 v[42:43], v[8:9], v[106:107], v[42:43]
	v_pk_fma_f32 v[46:47], v[10:11], v[108:109], v[46:47]
	v_pk_fma_f32 v[42:43], v[0:1], v[102:103], v[42:43]
	v_pk_fma_f32 v[46:47], v[2:3], v[104:105], v[46:47]
	v_pk_mul_f32 v[14:15], v[122:123], v[14:15]
	v_pk_mul_f32 v[12:13], v[124:125], v[12:13]
	v_pk_mul_f32 v[88:89], v[88:89], v[46:47]
	v_pk_mul_f32 v[86:87], v[86:87], v[42:43]
	v_cvt_pk_bf16_f32 v46, v14, v15
	v_cvt_pk_bf16_f32 v47, v38, v39
	v_cvt_pk_bf16_f32 v42, v12, v13
	v_cvt_pk_bf16_f32 v43, v34, v35
	v_cvt_pk_bf16_f32 v38, v82, v83
	v_cvt_pk_bf16_f32 v39, v84, v85
	s_nop 0
	v_cvt_pk_bf16_f32 v34, v86, v87
	v_cvt_pk_bf16_f32 v35, v88, v89
	s_and_saveexec_b64 s[8:9], s[0:1]
	s_cbranch_execz .LBB0_756
	v_mov_b64_e32 v[12:13], s[22:23]
	v_mad_i64_i32 v[14:15], s[10:11], v66, s56, v[12:13]
	v_mad_i64_i32 v[12:13], s[10:11], v68, s56, v[12:13]
	v_lshl_add_u64 v[14:15], v[14:15], 0, v[64:65]
	v_lshl_add_u64 v[12:13], v[12:13], 0, v[64:65]
	global_store_dwordx4 v[14:15], v[44:47], off
	global_store_dwordx4 v[12:13], v[40:43], off
